# scheduler parameters: 6 VALU per MFMA gap, earlier global-load placement in GQA PV
# baseline (speedup 1.0000x reference)
.LBB0_739:
	ds_read_b128 v[236:239], v200 offset:49152
	ds_read_b128 v[240:243], v208 offset:49152
	ds_read_b128 v[244:247], v207 offset:49152
	ds_read_b128 v[248:251], v206 offset:49152
	s_add_i32 s6, s14, -3
	s_waitcnt lgkmcnt(3)
	v_mfma_f32_32x32x16_bf16 v[80:95], v[236:239], v[124:127], 0
	ds_read_b128 v[236:239], v205 offset:49152
	v_exp_f32_e32 v158, v158
	v_exp_f32_e32 v159, v159
	v_exp_f32_e32 v156, v156
	s_waitcnt lgkmcnt(3)
	v_mfma_f32_32x32x16_bf16 v[80:95], v[240:243], v[120:123], v[80:95]
	ds_read_b128 v[240:243], v204 offset:49152
	v_exp_f32_e32 v157, v157
	v_exp_f32_e32 v150, v150
	v_exp_f32_e32 v151, v151
	s_waitcnt lgkmcnt(3)
	v_mfma_f32_32x32x16_bf16 v[80:95], v[244:247], v[116:119], v[80:95]
	ds_read_b128 v[244:247], v202 offset:49152
	v_exp_f32_e32 v148, v148
	v_exp_f32_e32 v149, v149
	v_exp_f32_e32 v146, v146
	s_waitcnt lgkmcnt(3)
	v_mfma_f32_32x32x16_bf16 v[80:95], v[248:251], v[112:115], v[80:95]
	ds_read_b128 v[248:251], v201 offset:49152
	v_exp_f32_e32 v147, v147
	v_exp_f32_e32 v160, v160
	v_exp_f32_e32 v161, v161
	s_waitcnt lgkmcnt(3)
	v_mfma_f32_32x32x16_bf16 v[80:95], v[236:239], v[108:111], v[80:95]
	ds_read_b128 v[236:239], v200 offset:57344
	v_exp_f32_e32 v154, v154
	v_exp_f32_e32 v155, v155
	v_exp_f32_e32 v152, v152
	s_waitcnt lgkmcnt(3)
	v_mfma_f32_32x32x16_bf16 v[80:95], v[240:243], v[104:107], v[80:95]
	ds_read_b128 v[240:243], v208 offset:57344
	v_exp_f32_e32 v153, v153
	v_add_f32_e32 v210, 0, v162
	v_add_f32_e32 v210, v216, v210
	v_add_f32_e32 v210, v163, v210
	v_add_f32_e32 v210, v177, v210
	s_waitcnt lgkmcnt(3)
	v_mfma_f32_32x32x16_bf16 v[80:95], v[244:247], v[100:103], v[80:95]
	ds_read_b128 v[244:247], v207 offset:57344
	v_add_f32_e32 v210, v164, v210
	v_add_f32_e32 v210, v176, v210
	v_add_f32_e32 v210, v165, v210
	v_add_f32_e32 v210, v175, v210
	v_add_f32_e32 v210, v166, v210
	v_add_f32_e32 v210, v173, v210
	s_waitcnt lgkmcnt(3)
	v_mfma_f32_32x32x16_bf16 v[80:95], v[248:251], v[96:99], v[80:95]
	ds_read_b128 v[248:251], v206 offset:57344
	v_add_f32_e32 v210, v167, v210
	v_add_f32_e32 v210, v172, v210
	v_add_f32_e32 v210, v168, v210
	v_add_f32_e32 v210, v171, v210
	v_add_f32_e32 v210, v169, v210
	v_add_f32_e32 v210, v170, v210
	s_waitcnt lgkmcnt(3)
	v_mfma_f32_32x32x16_bf16 v[64:79], v[236:239], v[124:127], 0
	ds_read_b128 v[236:239], v205 offset:57344
	v_add_f32_e32 v210, v158, v210
	v_add_f32_e32 v210, v159, v210
	v_add_f32_e32 v210, v156, v210
	v_add_f32_e32 v210, v157, v210
	v_add_f32_e32 v210, v150, v210
	v_add_f32_e32 v210, v151, v210
	s_waitcnt lgkmcnt(3)
	v_mfma_f32_32x32x16_bf16 v[64:79], v[240:243], v[120:123], v[64:79]
	ds_read_b128 v[240:243], v204 offset:57344
	v_add_f32_e32 v210, v148, v210
	v_add_f32_e32 v210, v149, v210
	v_add_f32_e32 v210, v146, v210
	v_add_f32_e32 v210, v147, v210
	v_add_f32_e32 v210, v160, v210
	v_add_f32_e32 v210, v161, v210
	s_waitcnt lgkmcnt(3)
	v_mfma_f32_32x32x16_bf16 v[64:79], v[244:247], v[116:119], v[64:79]
	ds_read_b128 v[244:247], v202 offset:57344
	v_add_f32_e32 v210, v154, v210
	v_add_f32_e32 v210, v155, v210
	v_add_f32_e32 v210, v152, v210
	v_add_f32_e32 v210, v153, v210
	v_mov_b32_e32 v211, v210
	v_cvt_pk_bf16_f32 v162, v162, v216
	s_waitcnt lgkmcnt(3)
	v_mfma_f32_32x32x16_bf16 v[64:79], v[248:251], v[112:115], v[64:79]
	ds_read_b128 v[248:251], v201 offset:57344
	ds_read_b64_tr_b16 v[216:217], v193 offset:0
	ds_read_b64_tr_b16 v[218:219], v193 offset:0x800
	ds_read_b64_tr_b16 v[220:221], v193 offset:0x1000
	ds_read_b64_tr_b16 v[222:223], v193 offset:0x1800
	ds_read_b64_tr_b16 v[224:225], v193 offset:0x2000
	ds_read_b64_tr_b16 v[226:227], v193 offset:0x2800
	ds_read_b64_tr_b16 v[232:233], v193 offset:0x3000
	ds_read_b64_tr_b16 v[234:235], v193 offset:0x3800
	v_cvt_pk_bf16_f32 v163, v163, v177
	v_cvt_pk_bf16_f32 v164, v164, v176
	v_permlane32_swap_b32_e32 v210, v211
	v_cvt_pk_bf16_f32 v165, v165, v175
	v_permlane32_swap_b32_e32 v162, v164
	v_cvt_pk_bf16_f32 v166, v166, v173
	s_waitcnt lgkmcnt(11)
	v_mfma_f32_32x32x16_bf16 v[64:79], v[236:239], v[108:111], v[64:79]
	v_cvt_pk_bf16_f32 v167, v167, v172
	v_cvt_pk_bf16_f32 v168, v168, v171
	v_cvt_pk_bf16_f32 v169, v169, v170
	v_cvt_pk_bf16_f32 v170, v158, v159
	v_cvt_pk_bf16_f32 v171, v156, v157
	v_cvt_pk_bf16_f32 v172, v150, v151
	s_waitcnt lgkmcnt(10)
	v_mfma_f32_32x32x16_bf16 v[64:79], v[240:243], v[104:107], v[64:79]
	v_cvt_pk_bf16_f32 v173, v148, v149
	v_cvt_pk_bf16_f32 v212, v146, v147
	v_cvt_pk_bf16_f32 v213, v160, v161
	v_cvt_pk_bf16_f32 v214, v154, v155
	v_cvt_pk_bf16_f32 v215, v152, v153
	v_permlane32_swap_b32_e32 v163, v165
	s_waitcnt lgkmcnt(9)
	v_mfma_f32_32x32x16_bf16 v[64:79], v[244:247], v[100:103], v[64:79]
	v_permlane32_swap_b32_e32 v166, v168
	v_permlane32_swap_b32_e32 v167, v169
	v_permlane32_swap_b32_e32 v170, v172
	v_permlane32_swap_b32_e32 v171, v173
	v_permlane32_swap_b32_e32 v212, v214
	v_permlane32_swap_b32_e32 v213, v215
	s_waitcnt lgkmcnt(8)
	v_mfma_f32_32x32x16_bf16 v[64:79], v[248:251], v[96:99], v[64:79]
	v_max_f32_e32 v250, v81, v81
	v_max_f32_e32 v251, v80, v80
	v_max_f32_e32 v250, v251, v250
	v_max3_f32 v250, v250, v82, v83
	v_max3_f32 v250, v250, v84, v85
	v_max3_f32 v250, v250, v86, v87
	s_waitcnt vmcnt(0)
	ds_write_b128 v198, v[136:139] offset:32768
	ds_write_b128 v199, v[140:143] offset:32768
	s_sub_i32 s7, s8, 64
	s_cmp_lt_u32 s6, 2
	s_cselect_b32 s6, s15, s7
	s_ashr_i32 s7, s6, 31
	s_waitcnt lgkmcnt(8)
	v_mfma_f32_32x32x16_bf16 v[48:63], v[162:165], v[216:219], v[48:63]
	ds_read_b64_tr_b16 v[216:217], v193 offset:0x200
	ds_read_b64_tr_b16 v[218:219], v193 offset:0xa00
	v_lshl_add_u64 v[146:147], s[6:7], 0, v[178:179]
	v_mul_lo_u32 v148, v147, s40
	v_mul_lo_u32 v149, v146, s41
	v_mad_u64_u32 v[146:147], s[10:11], v146, s40, 0
	v_add3_u32 v147, v147, v149, v148
	v_lshl_add_u64 v[148:149], v[180:181], 0, s[6:7]
	s_waitcnt lgkmcnt(8)
	v_mfma_f32_32x32x16_bf16 v[48:63], v[166:169], v[220:223], v[48:63]
	ds_read_b64_tr_b16 v[220:221], v193 offset:0x1200
	ds_read_b64_tr_b16 v[222:223], v193 offset:0x1a00
	v_mul_lo_u32 v150, v149, s40
	v_mul_lo_u32 v151, v148, s41
	v_mad_u64_u32 v[148:149], s[6:7], v148, s40, 0
	v_add3_u32 v149, v149, v151, v150
	v_lshlrev_b64 v[154:155], 1, v[146:147]
	v_lshlrev_b64 v[156:157], 1, v[148:149]
	s_waitcnt lgkmcnt(8)
	v_mfma_f32_32x32x16_bf16 v[48:63], v[170:173], v[224:227], v[48:63]
	ds_read_b64_tr_b16 v[224:225], v193 offset:0x2200
	ds_read_b64_tr_b16 v[226:227], v193 offset:0x2a00
	v_lshl_add_u64 v[146:147], v[182:183], 0, v[154:155]
	v_lshl_add_u64 v[150:151], v[182:183], 0, v[156:157]
	v_lshl_add_u64 v[154:155], v[184:185], 0, v[154:155]
	v_lshl_add_u64 v[158:159], v[184:185], 0, v[156:157]
	v_max3_f32 v250, v250, v88, v89
	v_max3_f32 v250, v250, v90, v91
	s_waitcnt lgkmcnt(8)
	v_mfma_f32_32x32x16_bf16 v[48:63], v[212:215], v[232:235], v[48:63]
	ds_read_b64_tr_b16 v[232:233], v193 offset:0x3200
	ds_read_b64_tr_b16 v[234:235], v193 offset:0x3a00
	v_max3_f32 v250, v250, v92, v93
	v_max3_f32 v250, v250, v94, v95
	v_max3_f32 v250, v250, v64, v65
	v_max3_f32 v250, v250, v66, v67
	v_max3_f32 v250, v250, v68, v69
	v_max3_f32 v250, v250, v70, v71
	global_load_dwordx4 v[146:149], v[146:147], off
	global_load_dwordx4 v[150:153], v[150:151], off
	global_load_dwordx4 v[154:157], v[154:155], off
	global_load_dwordx4 v[158:161], v[158:159], off
	s_waitcnt lgkmcnt(6)
	v_mfma_f32_32x32x16_bf16 v[32:47], v[162:165], v[216:219], v[32:47]
	ds_read_b64_tr_b16 v[216:217], v193 offset:0x400
	ds_read_b64_tr_b16 v[218:219], v193 offset:0xc00
	v_max3_f32 v250, v250, v72, v73
	v_max3_f32 v250, v250, v74, v75
	v_max3_f32 v250, v250, v76, v77
	v_max3_f32 v250, v250, v78, v79
	v_mov_b32_e32 v251, v250
	s_nop 1
	v_permlane32_swap_b32_e32 v250, v251
	s_waitcnt lgkmcnt(6)
	v_mfma_f32_32x32x16_bf16 v[32:47], v[166:169], v[220:223], v[32:47]
	ds_read_b64_tr_b16 v[220:221], v193 offset:0x1400
	ds_read_b64_tr_b16 v[222:223], v193 offset:0x1c00
	v_max_f32_e32 v251, v251, v251
	v_max_f32_e32 v250, v250, v250
	v_max_f32_e32 v250, v250, v251
	v_sub_f32_e32 v251, v250, v174
	v_cmp_ge_f32_e32 vcc, s93, v251
	v_max_f32_e32 v251, v174, v174
	s_waitcnt lgkmcnt(6)
	v_mfma_f32_32x32x16_bf16 v[32:47], v[170:173], v[224:227], v[32:47]
	ds_read_b64_tr_b16 v[224:225], v193 offset:0x2400
	ds_read_b64_tr_b16 v[226:227], v193 offset:0x2c00
	v_max_f32_e32 v250, v251, v250
	v_sub_f32_e32 v251, v174, v250
	v_mul_f32_e32 v251, 0x3e0293ee, v251
	v_exp_f32_e32 v251, v251
	s_waitcnt lgkmcnt(6)
	v_mfma_f32_32x32x16_bf16 v[32:47], v[212:215], v[232:235], v[32:47]
	ds_read_b64_tr_b16 v[232:233], v193 offset:0x3400
	ds_read_b64_tr_b16 v[234:235], v193 offset:0x3c00
	s_waitcnt lgkmcnt(6)
	v_mfma_f32_32x32x16_bf16 v[16:31], v[162:165], v[216:219], v[16:31]
	ds_read_b64_tr_b16 v[216:217], v193 offset:0x600
	ds_read_b64_tr_b16 v[218:219], v193 offset:0xe00
	s_waitcnt lgkmcnt(6)
	v_mfma_f32_32x32x16_bf16 v[16:31], v[166:169], v[220:223], v[16:31]
	ds_read_b64_tr_b16 v[220:221], v193 offset:0x1600
	ds_read_b64_tr_b16 v[222:223], v193 offset:0x1e00
	s_waitcnt lgkmcnt(6)
	v_mfma_f32_32x32x16_bf16 v[16:31], v[170:173], v[224:227], v[16:31]
	ds_read_b64_tr_b16 v[224:225], v193 offset:0x2600
	ds_read_b64_tr_b16 v[226:227], v193 offset:0x2e00
	s_waitcnt lgkmcnt(6)
	v_mfma_f32_32x32x16_bf16 v[16:31], v[212:215], v[232:235], v[16:31]
	ds_read_b64_tr_b16 v[232:233], v193 offset:0x3600
	ds_read_b64_tr_b16 v[234:235], v193 offset:0x3e00
	s_waitcnt lgkmcnt(6)
	v_mfma_f32_32x32x16_bf16 v[0:15], v[162:165], v[216:219], v[0:15]
	s_waitcnt lgkmcnt(4)
	v_mfma_f32_32x32x16_bf16 v[0:15], v[166:169], v[220:223], v[0:15]
	s_waitcnt lgkmcnt(2)
	v_mfma_f32_32x32x16_bf16 v[0:15], v[170:173], v[224:227], v[0:15]
	s_waitcnt lgkmcnt(0)
	v_mfma_f32_32x32x16_bf16 v[0:15], v[212:215], v[232:235], v[0:15]
	s_cmp_eq_u64 vcc, exec
	s_cselect_b64 s[6:7], -1, 0
	s_branch .Lgqa_joinA
.Lgqa_loopA:
	ds_read_b128 v[236:239], v200 offset:49152
	ds_read_b128 v[240:243], v208 offset:49152
	ds_read_b128 v[244:247], v207 offset:49152
	ds_read_b128 v[248:251], v206 offset:49152
	s_add_i32 s6, s14, -3
	s_waitcnt lgkmcnt(3)
	v_mfma_f32_32x32x16_bf16 v[80:95], v[236:239], v[124:127], 0
	ds_read_b128 v[236:239], v205 offset:49152
	v_exp_f32_e32 v162, v162
	v_exp_f32_e32 v216, v216
	v_exp_f32_e32 v163, v163
	s_waitcnt lgkmcnt(3)
	v_mfma_f32_32x32x16_bf16 v[80:95], v[240:243], v[120:123], v[80:95]
	ds_read_b128 v[240:243], v204 offset:49152
	v_exp_f32_e32 v177, v177
	v_exp_f32_e32 v164, v164
	v_exp_f32_e32 v176, v176
	s_waitcnt lgkmcnt(3)
	v_mfma_f32_32x32x16_bf16 v[80:95], v[244:247], v[116:119], v[80:95]
	ds_read_b128 v[244:247], v202 offset:49152
	v_exp_f32_e32 v165, v165
	v_exp_f32_e32 v175, v175
	v_exp_f32_e32 v166, v166
	s_waitcnt lgkmcnt(3)
	v_mfma_f32_32x32x16_bf16 v[80:95], v[248:251], v[112:115], v[80:95]
	ds_read_b128 v[248:251], v201 offset:49152
	v_exp_f32_e32 v173, v173
	v_exp_f32_e32 v167, v167
	v_exp_f32_e32 v172, v172
	s_waitcnt lgkmcnt(3)
	v_mfma_f32_32x32x16_bf16 v[80:95], v[236:239], v[108:111], v[80:95]
	ds_read_b128 v[236:239], v200 offset:57344
	v_exp_f32_e32 v168, v168
	v_exp_f32_e32 v171, v171
	v_exp_f32_e32 v169, v169
	s_waitcnt lgkmcnt(3)
	v_mfma_f32_32x32x16_bf16 v[80:95], v[240:243], v[104:107], v[80:95]
	ds_read_b128 v[240:243], v208 offset:57344
	v_exp_f32_e32 v170, v170
	v_pk_fma_f32 v[158:159], v[64:65], s[92:93], v[152:153] op_sel_hi:[1,0,0]
	v_pk_fma_f32 v[156:157], v[66:67], s[92:93], v[152:153] op_sel_hi:[1,0,0]
	v_pk_fma_f32 v[150:151], v[68:69], s[92:93], v[152:153] op_sel_hi:[1,0,0]
	v_pk_fma_f32 v[148:149], v[70:71], s[92:93], v[152:153] op_sel_hi:[1,0,0]
	s_waitcnt lgkmcnt(3)
	v_mfma_f32_32x32x16_bf16 v[80:95], v[244:247], v[100:103], v[80:95]
	ds_read_b128 v[244:247], v207 offset:57344
	v_pk_fma_f32 v[146:147], v[72:73], s[92:93], v[152:153] op_sel_hi:[1,0,0]
	v_pk_fma_f32 v[160:161], v[74:75], s[92:93], v[152:153] op_sel_hi:[1,0,0]
	v_pk_fma_f32 v[154:155], v[76:77], s[92:93], v[152:153] op_sel_hi:[1,0,0]
	v_pk_fma_f32 v[152:153], v[78:79], s[92:93], v[152:153] op_sel_hi:[1,0,0]
	v_exp_f32_e32 v158, v158
	s_waitcnt lgkmcnt(3)
	v_mfma_f32_32x32x16_bf16 v[80:95], v[248:251], v[96:99], v[80:95]
	ds_read_b128 v[248:251], v206 offset:57344
	v_exp_f32_e32 v159, v159
	v_exp_f32_e32 v156, v156
	v_exp_f32_e32 v157, v157
	s_waitcnt lgkmcnt(3)
	v_mfma_f32_32x32x16_bf16 v[64:79], v[236:239], v[124:127], 0
	ds_read_b128 v[236:239], v205 offset:57344
	v_exp_f32_e32 v150, v150
	v_exp_f32_e32 v151, v151
	v_exp_f32_e32 v148, v148
	s_waitcnt lgkmcnt(3)
	v_mfma_f32_32x32x16_bf16 v[64:79], v[240:243], v[120:123], v[64:79]
	ds_read_b128 v[240:243], v204 offset:57344
	v_exp_f32_e32 v149, v149
	v_exp_f32_e32 v146, v146
	v_exp_f32_e32 v147, v147
	s_waitcnt lgkmcnt(3)
	v_mfma_f32_32x32x16_bf16 v[64:79], v[244:247], v[116:119], v[64:79]
	ds_read_b128 v[244:247], v202 offset:57344
	v_exp_f32_e32 v160, v160
	v_exp_f32_e32 v161, v161
	v_exp_f32_e32 v154, v154
	s_waitcnt lgkmcnt(3)
	v_mfma_f32_32x32x16_bf16 v[64:79], v[248:251], v[112:115], v[64:79]
	ds_read_b128 v[248:251], v201 offset:57344
	v_exp_f32_e32 v155, v155
	v_exp_f32_e32 v152, v152
	v_exp_f32_e32 v153, v153
	s_waitcnt lgkmcnt(3)
	v_mfma_f32_32x32x16_bf16 v[64:79], v[236:239], v[108:111], v[64:79]
	v_add_f32_e32 v210, 0, v162
	v_add_f32_e32 v210, v216, v210
	v_add_f32_e32 v210, v163, v210
	v_add_f32_e32 v210, v177, v210
	v_add_f32_e32 v210, v164, v210
	v_add_f32_e32 v210, v176, v210
	s_waitcnt lgkmcnt(2)
	v_mfma_f32_32x32x16_bf16 v[64:79], v[240:243], v[104:107], v[64:79]
	v_add_f32_e32 v210, v165, v210
	v_add_f32_e32 v210, v175, v210
	v_add_f32_e32 v210, v166, v210
	v_add_f32_e32 v210, v173, v210
	v_add_f32_e32 v210, v167, v210
	v_add_f32_e32 v210, v172, v210
	s_waitcnt lgkmcnt(1)
	v_mfma_f32_32x32x16_bf16 v[64:79], v[244:247], v[100:103], v[64:79]
	v_add_f32_e32 v210, v168, v210
	v_add_f32_e32 v210, v171, v210
	v_add_f32_e32 v210, v169, v210
	v_add_f32_e32 v210, v170, v210
	v_add_f32_e32 v210, v158, v210
	v_add_f32_e32 v210, v159, v210
	s_waitcnt lgkmcnt(0)
	v_mfma_f32_32x32x16_bf16 v[64:79], v[248:251], v[96:99], v[64:79]
	v_add_f32_e32 v210, v156, v210
	v_add_f32_e32 v210, v157, v210
	v_add_f32_e32 v210, v150, v210
	v_add_f32_e32 v210, v151, v210
	v_add_f32_e32 v210, v148, v210
	v_add_f32_e32 v210, v149, v210
	s_waitcnt vmcnt(0)
	ds_write_b128 v198, v[136:139] offset:32768
	ds_write_b128 v199, v[140:143] offset:32768
	s_sub_i32 s7, s8, 64
	s_cmp_lt_u32 s6, 2
	s_cselect_b32 s6, s15, s7
	s_ashr_i32 s7, s6, 31
	v_cvt_pk_bf16_f32 v162, v162, v216
	v_cvt_pk_bf16_f32 v163, v163, v177
	v_cvt_pk_bf16_f32 v164, v164, v176
	v_cvt_pk_bf16_f32 v165, v165, v175
	s_nop 0
	v_permlane32_swap_b32_e32 v162, v164
	v_permlane32_swap_b32_e32 v163, v165
	ds_read_b64_tr_b16 v[216:217], v193 offset:0
	ds_read_b64_tr_b16 v[218:219], v193 offset:0x800
	s_waitcnt lgkmcnt(0)
	v_mfma_f32_32x32x16_bf16 v[48:63], v[162:165], v[216:219], v[48:63]
	ds_read_b64_tr_b16 v[220:221], v193 offset:0x1000
	ds_read_b64_tr_b16 v[222:223], v193 offset:0x1800
	ds_read_b64_tr_b16 v[224:225], v193 offset:0x2000
	ds_read_b64_tr_b16 v[226:227], v193 offset:0x2800
	ds_read_b64_tr_b16 v[232:233], v193 offset:0x3000
	ds_read_b64_tr_b16 v[234:235], v193 offset:0x3800
	ds_read_b64_tr_b16 v[216:217], v193 offset:0x200
	ds_read_b64_tr_b16 v[218:219], v193 offset:0xa00
	v_add_f32_e32 v210, v146, v210
	v_add_f32_e32 v210, v147, v210
	v_add_f32_e32 v210, v160, v210
	v_add_f32_e32 v210, v161, v210
	v_add_f32_e32 v210, v154, v210
	v_add_f32_e32 v210, v155, v210
	v_cvt_pk_bf16_f32 v166, v166, v173
	v_cvt_pk_bf16_f32 v167, v167, v172
	v_cvt_pk_bf16_f32 v168, v168, v171
	v_cvt_pk_bf16_f32 v169, v169, v170
	s_nop 0
	v_permlane32_swap_b32_e32 v166, v168
	v_permlane32_swap_b32_e32 v167, v169
	s_waitcnt lgkmcnt(6)
	s_nop 0
	v_mfma_f32_32x32x16_bf16 v[48:63], v[166:169], v[220:223], v[48:63]
	ds_read_b64_tr_b16 v[220:221], v193 offset:0x1200
	ds_read_b64_tr_b16 v[222:223], v193 offset:0x1a00
	v_add_f32_e32 v210, v152, v210
	v_add_f32_e32 v210, v153, v210
	v_mov_b32_e32 v211, v210
	s_nop 1
	v_permlane32_swap_b32_e32 v210, v211
	v_cvt_pk_bf16_f32 v170, v158, v159
	v_cvt_pk_bf16_f32 v171, v156, v157
	v_cvt_pk_bf16_f32 v172, v150, v151
	v_cvt_pk_bf16_f32 v173, v148, v149
	s_nop 0
	v_permlane32_swap_b32_e32 v170, v172
	v_permlane32_swap_b32_e32 v171, v173
	s_waitcnt lgkmcnt(6)
	s_nop 0
	v_mfma_f32_32x32x16_bf16 v[48:63], v[170:173], v[224:227], v[48:63]
	ds_read_b64_tr_b16 v[224:225], v193 offset:0x2200
	ds_read_b64_tr_b16 v[226:227], v193 offset:0x2a00
	v_cvt_pk_bf16_f32 v212, v146, v147
	v_cvt_pk_bf16_f32 v213, v160, v161
	v_cvt_pk_bf16_f32 v214, v154, v155
	v_cvt_pk_bf16_f32 v215, v152, v153
	s_nop 0
	v_permlane32_swap_b32_e32 v212, v214
	v_permlane32_swap_b32_e32 v213, v215
	s_waitcnt lgkmcnt(6)
	s_nop 0
	v_mfma_f32_32x32x16_bf16 v[48:63], v[212:215], v[232:235], v[48:63]
	ds_read_b64_tr_b16 v[232:233], v193 offset:0x3200
	ds_read_b64_tr_b16 v[234:235], v193 offset:0x3a00
	v_lshl_add_u64 v[146:147], s[6:7], 0, v[178:179]
	v_mul_lo_u32 v148, v147, s40
	v_mul_lo_u32 v149, v146, s41
	v_mad_u64_u32 v[146:147], s[10:11], v146, s40, 0
	v_add3_u32 v147, v147, v149, v148
	v_lshl_add_u64 v[148:149], v[180:181], 0, s[6:7]
	v_mul_lo_u32 v150, v149, s40
	v_mul_lo_u32 v151, v148, s41
	v_mad_u64_u32 v[148:149], s[6:7], v148, s40, 0
	v_add3_u32 v149, v149, v151, v150
	v_lshlrev_b64 v[154:155], 1, v[146:147]
	v_lshlrev_b64 v[156:157], 1, v[148:149]
	v_lshl_add_u64 v[146:147], v[182:183], 0, v[154:155]
	global_load_dwordx4 v[146:149], v[146:147], off
	v_lshl_add_u64 v[150:151], v[182:183], 0, v[156:157]
	global_load_dwordx4 v[150:153], v[150:151], off
	v_lshl_add_u64 v[154:155], v[184:185], 0, v[154:155]
	v_lshl_add_u64 v[158:159], v[184:185], 0, v[156:157]
	global_load_dwordx4 v[154:157], v[154:155], off
	global_load_dwordx4 v[158:161], v[158:159], off
	s_waitcnt lgkmcnt(6)
	v_mfma_f32_32x32x16_bf16 v[32:47], v[162:165], v[216:219], v[32:47]
	ds_read_b64_tr_b16 v[216:217], v193 offset:0x400
	ds_read_b64_tr_b16 v[218:219], v193 offset:0xc00
	v_max_f32_e32 v250, v81, v81
	v_max_f32_e32 v251, v80, v80
	v_max_f32_e32 v250, v251, v250
	v_max3_f32 v250, v250, v82, v83
	v_max3_f32 v250, v250, v84, v85
	v_max3_f32 v250, v250, v86, v87
	s_waitcnt lgkmcnt(6)
	v_mfma_f32_32x32x16_bf16 v[32:47], v[166:169], v[220:223], v[32:47]
	ds_read_b64_tr_b16 v[220:221], v193 offset:0x1400
	ds_read_b64_tr_b16 v[222:223], v193 offset:0x1c00
	v_max3_f32 v250, v250, v88, v89
	v_max3_f32 v250, v250, v90, v91
	v_max3_f32 v250, v250, v92, v93
	v_max3_f32 v250, v250, v94, v95
	v_max3_f32 v250, v250, v64, v65
	v_max3_f32 v250, v250, v66, v67
	s_waitcnt lgkmcnt(6)
	v_mfma_f32_32x32x16_bf16 v[32:47], v[170:173], v[224:227], v[32:47]
	ds_read_b64_tr_b16 v[224:225], v193 offset:0x2400
	ds_read_b64_tr_b16 v[226:227], v193 offset:0x2c00
	v_max3_f32 v250, v250, v68, v69
	v_max3_f32 v250, v250, v70, v71
	v_max3_f32 v250, v250, v72, v73
	v_max3_f32 v250, v250, v74, v75
	v_max3_f32 v250, v250, v76, v77
	v_max3_f32 v250, v250, v78, v79
	s_waitcnt lgkmcnt(6)
	v_mfma_f32_32x32x16_bf16 v[32:47], v[212:215], v[232:235], v[32:47]
	ds_read_b64_tr_b16 v[232:233], v193 offset:0x3400
	ds_read_b64_tr_b16 v[234:235], v193 offset:0x3c00
	v_mov_b32_e32 v251, v250
	s_nop 1
	v_permlane32_swap_b32_e32 v250, v251
	v_max_f32_e32 v251, v251, v251
	v_max_f32_e32 v250, v250, v250
	v_max_f32_e32 v250, v250, v251
	v_sub_f32_e32 v251, v250, v174
	s_waitcnt lgkmcnt(6)
	v_mfma_f32_32x32x16_bf16 v[16:31], v[162:165], v[216:219], v[16:31]
	ds_read_b64_tr_b16 v[216:217], v193 offset:0x600
	ds_read_b64_tr_b16 v[218:219], v193 offset:0xe00
	v_cmp_ge_f32_e32 vcc, s93, v251
	v_max_f32_e32 v251, v174, v174
	v_max_f32_e32 v250, v251, v250
	v_sub_f32_e32 v251, v174, v250
	v_mul_f32_e32 v251, 0x3e0293ee, v251
	s_waitcnt lgkmcnt(6)
	v_mfma_f32_32x32x16_bf16 v[16:31], v[166:169], v[220:223], v[16:31]
	ds_read_b64_tr_b16 v[220:221], v193 offset:0x1600
	ds_read_b64_tr_b16 v[222:223], v193 offset:0x1e00
	v_exp_f32_e32 v251, v251
	s_waitcnt lgkmcnt(6)
	v_mfma_f32_32x32x16_bf16 v[16:31], v[170:173], v[224:227], v[16:31]
	ds_read_b64_tr_b16 v[224:225], v193 offset:0x2600
	ds_read_b64_tr_b16 v[226:227], v193 offset:0x2e00
	s_waitcnt lgkmcnt(6)
	v_mfma_f32_32x32x16_bf16 v[16:31], v[212:215], v[232:235], v[16:31]
	ds_read_b64_tr_b16 v[232:233], v193 offset:0x3600
	ds_read_b64_tr_b16 v[234:235], v193 offset:0x3e00
	s_waitcnt lgkmcnt(6)
	v_mfma_f32_32x32x16_bf16 v[0:15], v[162:165], v[216:219], v[0:15]
	s_waitcnt lgkmcnt(4)
	v_mfma_f32_32x32x16_bf16 v[0:15], v[166:169], v[220:223], v[0:15]
	s_waitcnt lgkmcnt(2)
	v_mfma_f32_32x32x16_bf16 v[0:15], v[170:173], v[224:227], v[0:15]
	s_waitcnt lgkmcnt(0)
	v_mfma_f32_32x32x16_bf16 v[0:15], v[212:215], v[232:235], v[0:15]
	s_cmp_eq_u64 vcc, exec
	s_cselect_b64 s[6:7], -1, 0

.LBB0_743:
	v_cndmask_b32_e64 v216, v250, v174, s[6:7]
	v_mul_f32_e32 v212, 0xbe0293ee, v216
	v_fmamk_f32 v162, v80, 0x3e0293ee, v212
	v_fmamk_f32 v177, v81, 0x3e0293ee, v212
	v_fmamk_f32 v163, v82, 0x3e0293ee, v212
	v_fmamk_f32 v176, v83, 0x3e0293ee, v212
	v_fmamk_f32 v164, v84, 0x3e0293ee, v212
	v_fmamk_f32 v175, v85, 0x3e0293ee, v212
	v_fmamk_f32 v165, v86, 0x3e0293ee, v212
	v_fmamk_f32 v174, v87, 0x3e0293ee, v212
	v_fmamk_f32 v166, v88, 0x3e0293ee, v212
	v_fmamk_f32 v173, v89, 0x3e0293ee, v212
	v_fmamk_f32 v167, v90, 0x3e0293ee, v212
	v_fmamk_f32 v172, v91, 0x3e0293ee, v212
	v_fmamk_f32 v168, v92, 0x3e0293ee, v212
	v_fmamk_f32 v171, v93, 0x3e0293ee, v212
	v_fmamk_f32 v169, v94, 0x3e0293ee, v212
	v_fmamk_f32 v170, v95, 0x3e0293ee, v212
	ds_read_b128 v[240:243], v200 offset:32768
	ds_read_b128 v[244:247], v208 offset:32768
	ds_read_b128 v[248:251], v207 offset:32768
	s_waitcnt lgkmcnt(2)
	v_mfma_f32_32x32x16_bf16 v[80:95], v[240:243], v[124:127], 0
	ds_read_b128 v[240:243], v206 offset:32768
	v_exp_f32_e32 v162, v162
	v_exp_f32_e32 v177, v177
	v_exp_f32_e32 v163, v163
	s_waitcnt lgkmcnt(2)
	v_mfma_f32_32x32x16_bf16 v[80:95], v[244:247], v[120:123], v[80:95]
	ds_read_b128 v[244:247], v205 offset:32768
	v_exp_f32_e32 v176, v176
	v_exp_f32_e32 v164, v164
	v_exp_f32_e32 v175, v175
	s_waitcnt lgkmcnt(2)
	v_mfma_f32_32x32x16_bf16 v[80:95], v[248:251], v[116:119], v[80:95]
	ds_read_b128 v[248:251], v204 offset:32768
	v_exp_f32_e32 v165, v165
	v_exp_f32_e32 v174, v174
	v_exp_f32_e32 v166, v166
	s_waitcnt lgkmcnt(2)
	v_mfma_f32_32x32x16_bf16 v[80:95], v[240:243], v[112:115], v[80:95]
	ds_read_b128 v[240:243], v202 offset:32768
	v_exp_f32_e32 v173, v173
	v_exp_f32_e32 v167, v167
	v_exp_f32_e32 v172, v172
	s_waitcnt lgkmcnt(2)
	v_mfma_f32_32x32x16_bf16 v[80:95], v[244:247], v[108:111], v[80:95]
	ds_read_b128 v[244:247], v201 offset:32768
	v_exp_f32_e32 v168, v168
	v_exp_f32_e32 v171, v171
	v_exp_f32_e32 v169, v169
	s_waitcnt lgkmcnt(2)
	v_mfma_f32_32x32x16_bf16 v[80:95], v[248:251], v[104:107], v[80:95]
	ds_read_b128 v[248:251], v200 offset:40960
	v_exp_f32_e32 v170, v170
	v_fmamk_f32 v219, v70, 0x3e0293ee, v212
	v_fmamk_f32 v220, v71, 0x3e0293ee, v212
	v_fmamk_f32 v225, v64, 0x3e0293ee, v212
	v_fmamk_f32 v226, v65, 0x3e0293ee, v212
	s_waitcnt lgkmcnt(2)
	v_mfma_f32_32x32x16_bf16 v[80:95], v[240:243], v[100:103], v[80:95]
	ds_read_b128 v[240:243], v208 offset:40960
	v_fmamk_f32 v227, v66, 0x3e0293ee, v212
	v_fmamk_f32 v232, v67, 0x3e0293ee, v212
	v_fmamk_f32 v233, v68, 0x3e0293ee, v212
	v_fmamk_f32 v218, v69, 0x3e0293ee, v212
	v_fmamk_f32 v221, v72, 0x3e0293ee, v212
	v_fmamk_f32 v222, v73, 0x3e0293ee, v212
	s_waitcnt lgkmcnt(2)
	v_mfma_f32_32x32x16_bf16 v[80:95], v[244:247], v[96:99], v[80:95]
	ds_read_b128 v[244:247], v207 offset:40960
	v_fmamk_f32 v223, v74, 0x3e0293ee, v212
	v_fmamk_f32 v224, v75, 0x3e0293ee, v212
	v_fmamk_f32 v213, v76, 0x3e0293ee, v212
	v_fmamk_f32 v234, v77, 0x3e0293ee, v212
	v_fmamk_f32 v235, v78, 0x3e0293ee, v212
	v_fmac_f32_e32 v212, 0x3e0293ee, v79
	s_waitcnt lgkmcnt(2)
	v_mfma_f32_32x32x16_bf16 v[64:79], v[248:251], v[124:127], 0
	ds_read_b128 v[248:251], v206 offset:40960
	v_exp_f32_e32 v215, v226
	v_exp_f32_e32 v226, v232
	v_exp_f32_e32 v232, v219
	s_waitcnt lgkmcnt(2)
	v_mfma_f32_32x32x16_bf16 v[64:79], v[240:243], v[120:123], v[64:79]
	ds_read_b128 v[240:243], v205 offset:40960
	v_add_f32_e32 v219, 0, v162
	v_add_f32_e32 v219, v177, v219
	v_add_f32_e32 v219, v163, v219
	v_add_f32_e32 v219, v176, v219
	v_add_f32_e32 v219, v164, v219
	v_add_f32_e32 v219, v175, v219
	s_waitcnt lgkmcnt(2)
	v_mfma_f32_32x32x16_bf16 v[64:79], v[244:247], v[116:119], v[64:79]
	ds_read_b128 v[244:247], v204 offset:40960
	v_add_f32_e32 v219, v165, v219
	v_add_f32_e32 v219, v174, v219
	v_add_f32_e32 v219, v166, v219
	v_add_f32_e32 v219, v173, v219
	v_add_f32_e32 v219, v167, v219
	v_add_f32_e32 v219, v172, v219
	s_waitcnt lgkmcnt(2)
	v_mfma_f32_32x32x16_bf16 v[64:79], v[248:251], v[112:115], v[64:79]
	ds_read_b128 v[248:251], v202 offset:40960
	v_exp_f32_e32 v214, v225
	v_add_f32_e32 v219, v168, v219
	v_add_f32_e32 v219, v171, v219
	v_exp_f32_e32 v225, v227
	s_waitcnt lgkmcnt(2)
	v_mfma_f32_32x32x16_bf16 v[64:79], v[240:243], v[108:111], v[64:79]
	ds_read_b128 v[240:243], v201 offset:40960
	v_add_f32_e32 v219, v169, v219
	v_add_f32_e32 v219, v170, v219
	v_exp_f32_e32 v227, v233
	v_add_f32_e32 v219, v214, v219
	v_add_f32_e32 v219, v215, v219
	s_waitcnt lgkmcnt(2)
	v_mfma_f32_32x32x16_bf16 v[64:79], v[244:247], v[104:107], v[64:79]
	v_exp_f32_e32 v218, v218
	v_add_f32_e32 v219, v225, v219
	v_exp_f32_e32 v233, v220
	v_add_f32_e32 v219, v226, v219
	s_waitcnt lgkmcnt(1)
	v_mfma_f32_32x32x16_bf16 v[64:79], v[248:251], v[100:103], v[64:79]
	v_exp_f32_e32 v221, v221
	v_add_f32_e32 v219, v227, v219
	v_exp_f32_e32 v222, v222
	v_add_f32_e32 v219, v218, v219
	s_waitcnt lgkmcnt(0)
	v_mfma_f32_32x32x16_bf16 v[64:79], v[240:243], v[96:99], v[64:79]
	v_exp_f32_e32 v223, v223
	v_add_f32_e32 v219, v232, v219
	v_exp_f32_e32 v224, v224
	v_add_f32_e32 v219, v233, v219
	s_cmp_ge_u32 s14, s91
	s_cselect_b64 s[10:11], -1, 0
	s_waitcnt vmcnt(0)
	ds_write_b128 v198, v[154:157] offset:49152
	ds_write_b128 v199, v[158:161] offset:49152
	s_ashr_i32 s9, s8, 31
	v_exp_f32_e32 v213, v213
	v_add_f32_e32 v219, v221, v219
	v_exp_f32_e32 v234, v234
	v_add_f32_e32 v219, v222, v219
	v_exp_f32_e32 v235, v235
	v_add_f32_e32 v219, v223, v219
	v_exp_f32_e32 v212, v212
	v_add_f32_e32 v219, v224, v219
	v_add_f32_e32 v219, v213, v219
	v_add_f32_e32 v219, v234, v219
	v_add_f32_e32 v219, v235, v219
	v_add_f32_e32 v219, v212, v219
	v_cvt_pk_bf16_f32 v162, v162, v177
	v_cvt_pk_bf16_f32 v163, v163, v176
	v_cvt_pk_bf16_f32 v164, v164, v175
	v_cvt_pk_bf16_f32 v165, v165, v174
	v_cvt_pk_bf16_f32 v169, v169, v170
	v_cvt_pk_bf16_f32 v170, v214, v215
	v_cvt_pk_bf16_f32 v176, v213, v234
	v_cvt_pk_bf16_f32 v177, v235, v212
	v_permlane32_swap_b32_e32 v162, v164
	v_permlane32_swap_b32_e32 v163, v165
	ds_read_b64_tr_b16 v[212:213], v197 offset:0
	ds_read_b64_tr_b16 v[214:215], v197 offset:0x800
	s_waitcnt lgkmcnt(0)
	v_mfma_f32_32x32x16_bf16 v[48:63], v[162:165], v[212:215], v[48:63]
	v_mov_b32_e32 v220, v219
	s_nop 1
	v_permlane32_swap_b32_e32 v219, v220
	v_cvt_pk_bf16_f32 v166, v166, v173
	v_cvt_pk_bf16_f32 v167, v167, v172
	v_cvt_pk_bf16_f32 v168, v168, v171
	v_cvt_pk_bf16_f32 v171, v225, v226
	v_cvt_pk_bf16_f32 v174, v221, v222
	v_cvt_pk_bf16_f32 v175, v223, v224
	v_permlane32_swap_b32_e32 v166, v168
	v_permlane32_swap_b32_e32 v167, v169
	ds_read_b64_tr_b16 v[222:223], v197 offset:0x1000
	ds_read_b64_tr_b16 v[224:225], v197 offset:0x1800
	s_waitcnt lgkmcnt(0)
	v_mfma_f32_32x32x16_bf16 v[48:63], v[166:169], v[222:225], v[48:63]
	v_cvt_pk_bf16_f32 v172, v227, v218
	v_cvt_pk_bf16_f32 v173, v232, v233
	s_nop 0
	v_permlane32_swap_b32_e32 v170, v172
	v_permlane32_swap_b32_e32 v171, v173
	v_permlane32_swap_b32_e32 v174, v176
	v_permlane32_swap_b32_e32 v175, v177
	ds_read_b64_tr_b16 v[232:233], v197 offset:0x2000
	ds_read_b64_tr_b16 v[234:235], v197 offset:0x2800
	ds_read_b64_tr_b16 v[236:237], v197 offset:0x3000
	ds_read_b64_tr_b16 v[238:239], v197 offset:0x3800
	ds_read_b64_tr_b16 v[212:213], v197 offset:0x200
	ds_read_b64_tr_b16 v[214:215], v197 offset:0xa00
	ds_read_b64_tr_b16 v[222:223], v197 offset:0x1200
	ds_read_b64_tr_b16 v[224:225], v197 offset:0x1a00
	s_waitcnt lgkmcnt(6)
	v_mfma_f32_32x32x16_bf16 v[48:63], v[170:173], v[232:235], v[48:63]
	ds_read_b64_tr_b16 v[232:233], v197 offset:0x2200
	ds_read_b64_tr_b16 v[234:235], v197 offset:0x2a00
	v_lshl_add_u64 v[128:129], s[8:9], 0, v[178:179]
	v_mul_lo_u32 v130, v129, s40
	v_mul_lo_u32 v131, v128, s41
	v_mad_u64_u32 v[128:129], s[6:7], v128, s40, 0
	v_add3_u32 v129, v129, v131, v130
	v_lshl_add_u64 v[130:131], v[180:181], 0, s[8:9]
	s_waitcnt lgkmcnt(6)
	v_mfma_f32_32x32x16_bf16 v[48:63], v[174:177], v[236:239], v[48:63]
	ds_read_b64_tr_b16 v[236:237], v197 offset:0x3200
	ds_read_b64_tr_b16 v[238:239], v197 offset:0x3a00
	v_mul_lo_u32 v132, v131, s40
	v_mul_lo_u32 v133, v130, s41
	v_mad_u64_u32 v[130:131], s[6:7], v130, s40, 0
	v_add3_u32 v131, v131, v133, v132
	v_lshlrev_b64 v[136:137], 1, v[128:129]
	v_lshlrev_b64 v[138:139], 1, v[130:131]
	v_lshl_add_u64 v[128:129], v[182:183], 0, v[136:137]
	global_load_dwordx4 v[128:131], v[128:129], off
	v_lshl_add_u64 v[132:133], v[182:183], 0, v[138:139]
	global_load_dwordx4 v[132:135], v[132:133], off
	v_lshl_add_u64 v[136:137], v[184:185], 0, v[136:137]
	v_lshl_add_u64 v[140:141], v[184:185], 0, v[138:139]
	global_load_dwordx4 v[136:139], v[136:137], off
	global_load_dwordx4 v[140:143], v[140:141], off
	s_waitcnt lgkmcnt(6)
	v_mfma_f32_32x32x16_bf16 v[32:47], v[162:165], v[212:215], v[32:47]
	ds_read_b64_tr_b16 v[212:213], v197 offset:0x400
	ds_read_b64_tr_b16 v[214:215], v197 offset:0xc00
	v_max_f32_e32 v250, v81, v81
	v_max_f32_e32 v251, v80, v80
	v_max_f32_e32 v250, v251, v250
	v_max3_f32 v250, v250, v82, v83
	v_max3_f32 v250, v250, v84, v85
	v_max3_f32 v250, v250, v86, v87
	s_waitcnt lgkmcnt(6)
	v_mfma_f32_32x32x16_bf16 v[32:47], v[166:169], v[222:225], v[32:47]
	ds_read_b64_tr_b16 v[222:223], v197 offset:0x1400
	ds_read_b64_tr_b16 v[224:225], v197 offset:0x1c00
	v_max3_f32 v250, v250, v88, v89
	v_max3_f32 v250, v250, v90, v91
	v_max3_f32 v250, v250, v92, v93
	v_max3_f32 v250, v250, v94, v95
	v_max3_f32 v250, v250, v64, v65
	v_max3_f32 v250, v250, v66, v67
	s_waitcnt lgkmcnt(6)
	v_mfma_f32_32x32x16_bf16 v[32:47], v[170:173], v[232:235], v[32:47]
	ds_read_b64_tr_b16 v[232:233], v197 offset:0x2400
	ds_read_b64_tr_b16 v[234:235], v197 offset:0x2c00
	v_max3_f32 v250, v250, v68, v69
	v_max3_f32 v250, v250, v70, v71
	v_max3_f32 v250, v250, v72, v73
	v_max3_f32 v250, v250, v74, v75
	v_max3_f32 v250, v250, v76, v77
	v_max3_f32 v250, v250, v78, v79
	s_waitcnt lgkmcnt(6)
	v_mfma_f32_32x32x16_bf16 v[32:47], v[174:177], v[236:239], v[32:47]
	ds_read_b64_tr_b16 v[236:237], v197 offset:0x3400
	ds_read_b64_tr_b16 v[238:239], v197 offset:0x3c00
	v_mov_b32_e32 v251, v250
	s_nop 1
	v_permlane32_swap_b32_e32 v250, v251
	v_max_f32_e32 v251, v251, v251
	v_max_f32_e32 v250, v250, v250
	v_max_f32_e32 v250, v250, v251
	v_sub_f32_e32 v251, v250, v216
	s_waitcnt lgkmcnt(6)
	v_mfma_f32_32x32x16_bf16 v[16:31], v[162:165], v[212:215], v[16:31]
	ds_read_b64_tr_b16 v[212:213], v197 offset:0x600
	ds_read_b64_tr_b16 v[214:215], v197 offset:0xe00
	v_cmp_ge_f32_e32 vcc, s93, v251
	v_max_f32_e32 v251, v216, v216
	v_max_f32_e32 v250, v251, v250
	v_sub_f32_e32 v251, v216, v250
	v_mul_f32_e32 v251, 0x3e0293ee, v251
	s_waitcnt lgkmcnt(6)
	v_mfma_f32_32x32x16_bf16 v[16:31], v[166:169], v[222:225], v[16:31]
	ds_read_b64_tr_b16 v[222:223], v197 offset:0x1600
	ds_read_b64_tr_b16 v[224:225], v197 offset:0x1e00
	v_exp_f32_e32 v251, v251
	s_waitcnt lgkmcnt(6)
	v_mfma_f32_32x32x16_bf16 v[16:31], v[170:173], v[232:235], v[16:31]
	ds_read_b64_tr_b16 v[232:233], v197 offset:0x2600
	ds_read_b64_tr_b16 v[234:235], v197 offset:0x2e00
	s_waitcnt lgkmcnt(6)
	v_mfma_f32_32x32x16_bf16 v[16:31], v[174:177], v[236:239], v[16:31]
	ds_read_b64_tr_b16 v[236:237], v197 offset:0x3600
	ds_read_b64_tr_b16 v[238:239], v197 offset:0x3e00
	s_waitcnt lgkmcnt(6)
	v_mfma_f32_32x32x16_bf16 v[0:15], v[162:165], v[212:215], v[0:15]
	s_waitcnt lgkmcnt(4)
	v_mfma_f32_32x32x16_bf16 v[0:15], v[166:169], v[222:225], v[0:15]
	s_waitcnt lgkmcnt(2)
	v_mfma_f32_32x32x16_bf16 v[0:15], v[170:173], v[232:235], v[0:15]
	s_waitcnt lgkmcnt(0)
	v_mfma_f32_32x32x16_bf16 v[0:15], v[174:177], v[236:239], v[0:15]
	s_cmp_eq_u64 vcc, exec
	s_cselect_b64 s[6:7], -1, 0
	s_barrier
	v_cndmask_b32_e64 v218, v251, 1.0, s[6:7]
	v_cmp_gt_f32_e32 vcc, 1.0, v218
	ds_write_b128 v195, v[146:149] offset:16384
	ds_write_b128 v196, v[150:153] offset:16384
	s_cbranch_vccz .LBB0_749
	s_and_saveexec_b64 s[12:13], s[4:5]
	ds_write_b32 v194, v218 offset:128
	s_or_b64 exec, exec, s[12:13]
	s_waitcnt lgkmcnt(0)
	v_add_u32_e32 v158, v192, v144
	ds_read_b128 v[146:149], v158 offset:224
	ds_read_b128 v[150:153], v158 offset:192
	ds_read_b128 v[154:157], v158 offset:160
	ds_read_b128 v[158:161], v158 offset:128
	s_waitcnt lgkmcnt(3)
	v_pk_mul_f32 v[60:61], v[60:61], v[146:147]
	s_waitcnt lgkmcnt(2)
	v_pk_mul_f32 v[56:57], v[56:57], v[150:151]
	s_waitcnt lgkmcnt(1)
	v_pk_mul_f32 v[52:53], v[52:53], v[154:155]
	v_pk_mul_f32 v[62:63], v[62:63], v[148:149]
	v_pk_mul_f32 v[58:59], v[58:59], v[152:153]
	v_pk_mul_f32 v[54:55], v[54:55], v[156:157]
	s_waitcnt lgkmcnt(0)
	v_pk_mul_f32 v[50:51], v[50:51], v[160:161]
	v_pk_mul_f32 v[48:49], v[48:49], v[158:159]
	v_pk_mul_f32 v[44:45], v[44:45], v[146:147]
	v_pk_mul_f32 v[40:41], v[40:41], v[150:151]
	v_pk_mul_f32 v[36:37], v[36:37], v[154:155]
	v_pk_mul_f32 v[46:47], v[46:47], v[148:149]
	v_pk_mul_f32 v[42:43], v[42:43], v[152:153]
	v_pk_mul_f32 v[38:39], v[38:39], v[156:157]
	v_pk_mul_f32 v[34:35], v[34:35], v[160:161]
	v_pk_mul_f32 v[32:33], v[32:33], v[158:159]
	v_pk_mul_f32 v[28:29], v[28:29], v[146:147]
	v_pk_mul_f32 v[24:25], v[24:25], v[150:151]
	v_pk_mul_f32 v[20:21], v[20:21], v[154:155]
	v_pk_mul_f32 v[30:31], v[30:31], v[148:149]
	v_pk_mul_f32 v[26:27], v[26:27], v[152:153]
	v_pk_mul_f32 v[22:23], v[22:23], v[156:157]
	v_pk_mul_f32 v[18:19], v[18:19], v[160:161]
	v_pk_mul_f32 v[16:17], v[16:17], v[158:159]
	v_pk_mul_f32 v[12:13], v[12:13], v[146:147]
	v_pk_mul_f32 v[8:9], v[8:9], v[150:151]
	v_pk_mul_f32 v[4:5], v[4:5], v[154:155]
	v_pk_mul_f32 v[14:15], v[14:15], v[148:149]
	v_pk_mul_f32 v[10:11], v[10:11], v[152:153]
	v_pk_mul_f32 v[6:7], v[6:7], v[156:157]
	v_pk_mul_f32 v[2:3], v[2:3], v[160:161]
	v_pk_mul_f32 v[0:1], v[0:1], v[158:159]

.LBB0_762:
	ds_read_b128 v[64:67], v189 offset:49152
	ds_read_b128 v[68:71], v189 offset:57344
	ds_read_b128 v[236:239], v191 offset:49152
	ds_read_b128 v[240:243], v191 offset:57344
	ds_read_b128 v[244:247], v193 offset:49152
	ds_read_b128 v[248:251], v193 offset:57344
	s_add_i32 s9, s24, -1
	s_cmp_lt_u32 s9, 3
	s_cselect_b32 s100, s46, s68
	s_add_i32 s100, s100, s8
	s_ashr_i32 s101, s100, 31
	s_add_i32 s0, 0, 0x12800
	s_waitcnt lgkmcnt(5)
	v_mfma_f32_32x32x16_bf16 v[80:95], v[64:67], v[124:127], 0
	v_exp_f32_e32 v140, v140
	v_exp_f32_e32 v141, v141
	v_exp_f32_e32 v138, v138
	s_waitcnt lgkmcnt(4)
	v_mfma_f32_32x32x16_bf16 v[64:79], v[68:71], v[124:127], 0
	v_exp_f32_e32 v139, v139
	v_exp_f32_e32 v214, v130
	v_exp_f32_e32 v215, v131
	s_waitcnt lgkmcnt(3)
	v_mfma_f32_32x32x16_bf16 v[80:95], v[236:239], v[120:123], v[80:95]
	ds_read_b128 v[236:239], v195 offset:49152
	v_exp_f32_e32 v142, v142
	v_exp_f32_e32 v143, v143
	v_exp_f32_e32 v136, v136
	s_waitcnt lgkmcnt(3)
	v_mfma_f32_32x32x16_bf16 v[64:79], v[240:243], v[120:123], v[64:79]
	ds_read_b128 v[240:243], v195 offset:57344
	v_exp_f32_e32 v137, v137
	v_add_u32_e32 v211, s0, v198
	v_add_u32_e32 v210, s0, v200
	v_exp_f32_e32 v212, v132
	s_waitcnt lgkmcnt(3)
	v_mfma_f32_32x32x16_bf16 v[80:95], v[244:247], v[116:119], v[80:95]
	ds_read_b128 v[244:247], v196 offset:49152
	v_exp_f32_e32 v213, v133
	v_add_u32_e32 v216, s0, v202
	v_add_u32_e32 v217, s0, v204
	v_exp_f32_e32 v220, v128
	s_waitcnt lgkmcnt(3)
	v_mfma_f32_32x32x16_bf16 v[64:79], v[248:251], v[116:119], v[64:79]
	ds_read_b128 v[248:251], v196 offset:57344
	v_add_f32_e32 v128, 0, v159
	v_add_f32_e32 v128, v161, v128
	v_add_f32_e32 v128, v157, v128
	v_add_f32_e32 v128, v160, v128
	v_add_f32_e32 v128, v156, v128
	v_add_f32_e32 v128, v158, v128
	s_waitcnt lgkmcnt(3)
	v_mfma_f32_32x32x16_bf16 v[80:95], v[236:239], v[112:115], v[80:95]
	ds_read_b128 v[236:239], v194 offset:49152
	v_add_f32_e32 v128, v154, v128
	v_add_f32_e32 v128, v155, v128
	v_add_f32_e32 v128, v151, v128
	v_add_f32_e32 v128, v153, v128
	v_add_f32_e32 v128, v150, v128
	v_add_f32_e32 v128, v152, v128
	s_waitcnt lgkmcnt(3)
	v_mfma_f32_32x32x16_bf16 v[64:79], v[240:243], v[112:115], v[64:79]
	ds_read_b128 v[240:243], v194 offset:57344
	v_add_f32_e32 v128, v147, v128
	v_add_f32_e32 v128, v149, v128
	v_add_f32_e32 v128, v146, v128
	v_add_f32_e32 v128, v148, v128
	v_add_f32_e32 v128, v140, v128
	v_add_f32_e32 v128, v141, v128
	s_waitcnt lgkmcnt(3)
	v_mfma_f32_32x32x16_bf16 v[80:95], v[244:247], v[108:111], v[80:95]
	ds_read_b128 v[244:247], v192 offset:49152
	v_add_f32_e32 v128, v138, v128
	v_add_f32_e32 v128, v139, v128
	v_add_f32_e32 v128, v212, v128
	v_exp_f32_e32 v221, v129
	v_add_f32_e32 v128, v213, v128
	s_waitcnt lgkmcnt(3)
	v_mfma_f32_32x32x16_bf16 v[64:79], v[248:251], v[108:111], v[64:79]
	ds_read_b128 v[248:251], v192 offset:57344
	v_add_f32_e32 v128, v214, v128
	v_add_f32_e32 v128, v215, v128
	v_add_f32_e32 v128, v220, v128
	v_add_f32_e32 v128, v221, v128
	v_exp_f32_e32 v223, v134
	s_waitcnt lgkmcnt(3)
	v_mfma_f32_32x32x16_bf16 v[80:95], v[236:239], v[104:107], v[80:95]
	ds_read_b128 v[236:239], v190 offset:49152
	v_add_f32_e32 v128, v142, v128
	v_exp_f32_e32 v224, v135
	v_add_f32_e32 v128, v143, v128
	v_add_f32_e32 v128, v136, v128
	v_add_f32_e32 v128, v137, v128
	s_waitcnt lgkmcnt(3)
	v_mfma_f32_32x32x16_bf16 v[64:79], v[240:243], v[104:107], v[64:79]
	ds_read_b128 v[240:243], v190 offset:57344
	v_add_f32_e32 v128, v223, v128
	v_add_f32_e32 v218, v224, v128
	v_mov_b32_e32 v219, v218
	v_cvt_pk_bf16_f32 v128, v159, v161
	v_cvt_pk_bf16_f32 v129, v157, v160
	v_cvt_pk_bf16_f32 v130, v156, v158
	s_waitcnt lgkmcnt(3)
	v_mfma_f32_32x32x16_bf16 v[80:95], v[244:247], v[100:103], v[80:95]
	ds_read_b128 v[244:247], v211
	v_cvt_pk_bf16_f32 v131, v154, v155
	v_cvt_pk_bf16_f32 v132, v151, v153
	v_cvt_pk_bf16_f32 v133, v150, v152
	v_cvt_pk_bf16_f32 v134, v147, v149
	v_cvt_pk_bf16_f32 v135, v146, v148
	v_cvt_pk_bf16_f32 v154, v140, v141
	s_waitcnt lgkmcnt(3)
	v_mfma_f32_32x32x16_bf16 v[64:79], v[248:251], v[100:103], v[64:79]
	v_cvt_pk_bf16_f32 v155, v138, v139
	v_cvt_pk_bf16_f32 v156, v212, v213
	v_cvt_pk_bf16_f32 v157, v214, v215
	v_cvt_pk_bf16_f32 v220, v220, v221
	v_cvt_pk_bf16_f32 v221, v142, v143
	v_cvt_pk_bf16_f32 v222, v136, v137
	s_waitcnt lgkmcnt(2)
	v_mfma_f32_32x32x16_bf16 v[80:95], v[236:239], v[96:99], v[80:95]
	ds_read_b128 v[236:239], v211 offset:4096
	ds_read_b128 v[248:251], v182
	v_permlane32_swap_b32_e32 v218, v219
	v_permlane32_swap_b32_e32 v128, v130
	v_cvt_pk_bf16_f32 v223, v223, v224
	v_permlane32_swap_b32_e32 v220, v222
	v_permlane32_swap_b32_e32 v129, v131
	v_permlane32_swap_b32_e32 v132, v134
	s_waitcnt lgkmcnt(3)
	v_mfma_f32_32x32x16_bf16 v[64:79], v[240:243], v[96:99], v[64:79]
	ds_read_b128 v[240:243], v210
	v_permlane32_swap_b32_e32 v133, v135
	v_permlane32_swap_b32_e32 v154, v156
	v_permlane32_swap_b32_e32 v155, v157
	v_permlane32_swap_b32_e32 v221, v223
	v_lshl_add_u64 v[136:137], s[100:101], 0, v[162:163]
	v_mul_lo_u32 v138, v137, s40
	s_waitcnt lgkmcnt(1)
	v_mfma_f32_32x32x16_bf16 v[80:95], v[244:247], v[248:251], v[80:95]
	v_mul_lo_u32 v139, v136, s41
	v_mad_u64_u32 v[136:137], s[6:7], v136, s40, 0
	v_add3_u32 v137, v137, v139, v138
	v_lshl_add_u64 v[138:139], v[166:167], 0, s[100:101]
	v_mul_lo_u32 v140, v139, s40
	v_mul_lo_u32 v141, v138, s41
	v_mfma_f32_32x32x16_bf16 v[64:79], v[236:239], v[248:251], v[64:79]
	ds_read_b128 v[248:251], v210 offset:4096
	ds_read_b128 v[244:247], v182 offset:1024
	ds_read_b128 v[236:239], v216
	v_mad_u64_u32 v[138:139], s[6:7], v138, s40, 0
	v_add3_u32 v139, v139, v141, v140
	v_lshlrev_b64 v[146:147], 1, v[136:137]
	v_lshlrev_b64 v[148:149], 1, v[138:139]
	v_lshl_add_u64 v[158:159], s[100:101], 0, v[164:165]
	v_lshl_add_u64 v[136:137], v[168:169], 0, v[146:147]
	s_waitcnt lgkmcnt(1)
	v_mfma_f32_32x32x16_bf16 v[80:95], v[240:243], v[244:247], v[80:95]
	v_lshl_add_u64 v[140:141], v[168:169], 0, v[148:149]
	v_lshl_add_u64 v[146:147], v[170:171], 0, v[146:147]
	v_lshl_add_u64 v[150:151], v[170:171], 0, v[148:149]
	v_mad_u64_u32 v[160:161], s[100:101], v158, s3, v[172:173]
	v_mad_i32_i24 v161, v159, s3, v161
	v_mfma_f32_32x32x16_bf16 v[64:79], v[248:251], v[244:247], v[64:79]
	ds_read_b128 v[244:247], v216 offset:4096
	ds_read_b128 v[240:243], v182 offset:2048
	ds_read_b128 v[248:251], v217
	s_waitcnt lgkmcnt(1)
	v_mfma_f32_32x32x16_bf16 v[80:95], v[236:239], v[240:243], v[80:95]
	v_mfma_f32_32x32x16_bf16 v[64:79], v[244:247], v[240:243], v[64:79]
	ds_read_b128 v[240:243], v217 offset:4096
	ds_read_b128 v[236:239], v182 offset:3072
	ds_read_b64_tr_b16 v[224:225], v181 offset:0
	ds_read_b64_tr_b16 v[226:227], v181 offset:0x800
	ds_read_b64_tr_b16 v[232:233], v181 offset:0x1000
	ds_read_b64_tr_b16 v[234:235], v181 offset:0x1800
	s_waitcnt lgkmcnt(4)
	v_mfma_f32_32x32x16_bf16 v[80:95], v[248:251], v[236:239], v[80:95]
	v_mfma_f32_32x32x16_bf16 v[64:79], v[240:243], v[236:239], v[64:79]
	ds_read_b64_tr_b16 v[236:237], v181 offset:0x2000
	ds_read_b64_tr_b16 v[238:239], v181 offset:0x2800
	ds_read_b64_tr_b16 v[240:241], v181 offset:0x3000
	ds_read_b64_tr_b16 v[242:243], v181 offset:0x3800
	ds_read_b64_tr_b16 v[212:213], v181 offset:0x200
	ds_read_b64_tr_b16 v[214:215], v181 offset:0xa00
	global_load_dwordx4 v[136:139], v[136:137], off
	global_load_dwordx4 v[140:143], v[140:141], off
	global_load_dwordx4 v[146:149], v[146:147], off
	global_load_dwordx4 v[150:153], v[150:151], off
	global_load_dwordx4 v[158:161], v[160:161], off
	s_waitcnt lgkmcnt(8)
	v_mfma_f32_32x32x16_bf16 v[0:15], v[128:131], v[224:227], v[0:15]
	ds_read_b64_tr_b16 v[224:225], v181 offset:0x1200
	ds_read_b64_tr_b16 v[226:227], v181 offset:0x1a00
	v_max_f32_e32 v250, v81, v81
	v_max_f32_e32 v251, v80, v80
	v_max_f32_e32 v250, v251, v250
	v_max3_f32 v250, v250, v82, v83
	v_max3_f32 v250, v250, v84, v85
	v_max3_f32 v250, v250, v86, v87
	s_waitcnt lgkmcnt(8)
	v_mfma_f32_32x32x16_bf16 v[0:15], v[132:135], v[232:235], v[0:15]
	ds_read_b64_tr_b16 v[232:233], v181 offset:0x2200
	ds_read_b64_tr_b16 v[234:235], v181 offset:0x2a00
	v_max3_f32 v250, v250, v88, v89
	v_max3_f32 v250, v250, v90, v91
	v_max3_f32 v250, v250, v92, v93
	v_max3_f32 v250, v250, v94, v95
	v_max3_f32 v250, v250, v64, v65
	v_max3_f32 v250, v250, v66, v67
	s_waitcnt lgkmcnt(8)
	v_mfma_f32_32x32x16_bf16 v[0:15], v[154:157], v[236:239], v[0:15]
	ds_read_b64_tr_b16 v[236:237], v181 offset:0x3200
	ds_read_b64_tr_b16 v[238:239], v181 offset:0x3a00
	v_max3_f32 v250, v250, v68, v69
	v_max3_f32 v250, v250, v70, v71
	v_max3_f32 v250, v250, v72, v73
	v_max3_f32 v250, v250, v74, v75
	v_max3_f32 v250, v250, v76, v77
	v_max3_f32 v250, v250, v78, v79
	s_waitcnt lgkmcnt(8)
	v_mfma_f32_32x32x16_bf16 v[0:15], v[220:223], v[240:243], v[0:15]
	ds_read_b64_tr_b16 v[240:241], v181 offset:0x400
	ds_read_b64_tr_b16 v[242:243], v181 offset:0xc00
	v_mov_b32_e32 v251, v250
	s_nop 1
	v_permlane32_swap_b32_e32 v250, v251
	v_max_f32_e32 v251, v251, v251
	v_max_f32_e32 v250, v250, v250
	v_max_f32_e32 v250, v250, v251
	v_sub_f32_e32 v251, v250, v207
	s_waitcnt lgkmcnt(8)
	v_mfma_f32_32x32x16_bf16 v[48:63], v[128:131], v[212:215], v[48:63]
	ds_read_b64_tr_b16 v[212:213], v181 offset:0x1400
	ds_read_b64_tr_b16 v[214:215], v181 offset:0x1c00
	v_cmp_ge_f32_e32 vcc, s94, v251
	v_max_f32_e32 v251, v207, v207
	v_max_f32_e32 v250, v251, v250
	v_sub_f32_e32 v251, v207, v250
	v_mul_f32_e32 v251, 0x3dd53b94, v251
	s_waitcnt lgkmcnt(8)
	v_mfma_f32_32x32x16_bf16 v[48:63], v[132:135], v[224:227], v[48:63]
	ds_read_b64_tr_b16 v[224:225], v181 offset:0x2400
	ds_read_b64_tr_b16 v[226:227], v181 offset:0x2c00
	v_exp_f32_e32 v251, v251
	s_waitcnt lgkmcnt(8)
	v_mfma_f32_32x32x16_bf16 v[48:63], v[154:157], v[232:235], v[48:63]
	ds_read_b64_tr_b16 v[232:233], v181 offset:0x3400
	ds_read_b64_tr_b16 v[234:235], v181 offset:0x3c00
	s_waitcnt lgkmcnt(8)
	v_mfma_f32_32x32x16_bf16 v[48:63], v[220:223], v[236:239], v[48:63]
	ds_read_b64_tr_b16 v[236:237], v181 offset:0x600
	ds_read_b64_tr_b16 v[238:239], v181 offset:0xe00
	s_waitcnt lgkmcnt(8)
	v_mfma_f32_32x32x16_bf16 v[32:47], v[128:131], v[240:243], v[32:47]
	ds_read_b64_tr_b16 v[240:241], v181 offset:0x1600
	ds_read_b64_tr_b16 v[242:243], v181 offset:0x1e00
	s_waitcnt lgkmcnt(8)
	v_mfma_f32_32x32x16_bf16 v[32:47], v[132:135], v[212:215], v[32:47]
	ds_read_b64_tr_b16 v[212:213], v181 offset:0x2600
	ds_read_b64_tr_b16 v[214:215], v181 offset:0x2e00
	s_waitcnt lgkmcnt(8)
	v_mfma_f32_32x32x16_bf16 v[32:47], v[154:157], v[224:227], v[32:47]
	ds_read_b64_tr_b16 v[224:225], v181 offset:0x3600
	ds_read_b64_tr_b16 v[226:227], v181 offset:0x3e00
	s_waitcnt lgkmcnt(8)
	v_mfma_f32_32x32x16_bf16 v[32:47], v[220:223], v[232:235], v[32:47]
	s_waitcnt lgkmcnt(6)
	v_mfma_f32_32x32x16_bf16 v[16:31], v[128:131], v[236:239], v[16:31]
	s_waitcnt lgkmcnt(4)
	v_mfma_f32_32x32x16_bf16 v[16:31], v[132:135], v[240:243], v[16:31]
	s_waitcnt lgkmcnt(2)
	v_mfma_f32_32x32x16_bf16 v[16:31], v[154:157], v[212:215], v[16:31]
	s_waitcnt lgkmcnt(0)
	v_mfma_f32_32x32x16_bf16 v[16:31], v[220:223], v[224:227], v[16:31]
	s_cmp_eq_u64 vcc, exec
	s_cselect_b64 s[6:7], -1, 0
	s_barrier
	s_waitcnt vmcnt(0)
	v_cndmask_b32_e64 v220, v251, 1.0, s[6:7]
	v_add_u32_e32 v129, 0x10800, v208
	v_cmp_gt_f32_e32 vcc, 1.0, v220
	ds_write_b128 v187, v[146:149] offset:32768
	ds_write_b128 v188, v[150:153] offset:32768
	ds_write_b128 v129, v[158:161]
	ds_write_b128 v185, v[136:139]
	ds_write_b128 v186, v[140:143]
	s_nop 0
	s_nop 0
	s_nop 0
	s_nop 0
	s_nop 0
	s_cbranch_vccz .LBB0_766
	s_and_saveexec_b64 s[0:1], s[4:5]
	ds_write_b32 v183, v220 offset:128
	s_or_b64 exec, exec, s[0:1]
	s_waitcnt lgkmcnt(0)
	v_add_u32_e32 v129, v180, v144
	ds_read_b128 v[130:133], v129 offset:224
	ds_read_b128 v[134:137], v129 offset:192
	ds_read_b128 v[138:141], v129 offset:160
	ds_read_b128 v[146:149], v129 offset:128
	s_waitcnt lgkmcnt(3)
	v_pk_mul_f32 v[12:13], v[12:13], v[130:131]
	s_waitcnt lgkmcnt(2)
	v_pk_mul_f32 v[8:9], v[8:9], v[134:135]
	s_waitcnt lgkmcnt(1)
	v_pk_mul_f32 v[4:5], v[4:5], v[138:139]
	v_pk_mul_f32 v[14:15], v[14:15], v[132:133]
	v_pk_mul_f32 v[10:11], v[10:11], v[136:137]
	v_pk_mul_f32 v[6:7], v[6:7], v[140:141]
	s_waitcnt lgkmcnt(0)
	v_pk_mul_f32 v[2:3], v[2:3], v[148:149]
	v_pk_mul_f32 v[0:1], v[0:1], v[146:147]
	v_pk_mul_f32 v[60:61], v[60:61], v[130:131]
	v_pk_mul_f32 v[56:57], v[56:57], v[134:135]
	v_pk_mul_f32 v[52:53], v[52:53], v[138:139]
	v_pk_mul_f32 v[62:63], v[62:63], v[132:133]
	v_pk_mul_f32 v[58:59], v[58:59], v[136:137]
	v_pk_mul_f32 v[54:55], v[54:55], v[140:141]
	v_pk_mul_f32 v[50:51], v[50:51], v[148:149]
	v_pk_mul_f32 v[48:49], v[48:49], v[146:147]
	v_pk_mul_f32 v[44:45], v[44:45], v[130:131]
	v_pk_mul_f32 v[40:41], v[40:41], v[134:135]
	v_pk_mul_f32 v[36:37], v[36:37], v[138:139]
	v_pk_mul_f32 v[46:47], v[46:47], v[132:133]
	v_pk_mul_f32 v[42:43], v[42:43], v[136:137]
	v_pk_mul_f32 v[38:39], v[38:39], v[140:141]
	v_pk_mul_f32 v[34:35], v[34:35], v[148:149]
	v_pk_mul_f32 v[32:33], v[32:33], v[146:147]
	v_pk_mul_f32 v[28:29], v[28:29], v[130:131]
	v_pk_mul_f32 v[24:25], v[24:25], v[134:135]
	v_pk_mul_f32 v[20:21], v[20:21], v[138:139]
	v_pk_mul_f32 v[30:31], v[30:31], v[132:133]
	v_pk_mul_f32 v[26:27], v[26:27], v[136:137]
	v_pk_mul_f32 v[22:23], v[22:23], v[140:141]
	v_pk_mul_f32 v[18:19], v[18:19], v[148:149]
	v_pk_mul_f32 v[16:17], v[16:17], v[146:147]
.LBB0_766:
	v_cndmask_b32_e64 v207, v250, v207, s[6:7]
	v_mul_f32_e32 v146, 0xbdd53b94, v207
	v_fmamk_f32 v80, v80, 0x3dd53b94, v146
	v_exp_f32_e32 v128, v80
	v_fmamk_f32 v81, v81, 0x3dd53b94, v146
	v_fmamk_f32 v82, v82, 0x3dd53b94, v146
	v_fmamk_f32 v83, v83, 0x3dd53b94, v146
	v_fmamk_f32 v84, v84, 0x3dd53b94, v146
	v_fmamk_f32 v85, v85, 0x3dd53b94, v146
	v_fmamk_f32 v86, v86, 0x3dd53b94, v146
	v_fmamk_f32 v87, v87, 0x3dd53b94, v146
	v_fmamk_f32 v88, v88, 0x3dd53b94, v146
	v_fmamk_f32 v89, v89, 0x3dd53b94, v146
	v_fmamk_f32 v90, v90, 0x3dd53b94, v146
	v_fmamk_f32 v91, v91, 0x3dd53b94, v146
	v_fmamk_f32 v92, v92, 0x3dd53b94, v146
	v_fmamk_f32 v93, v93, 0x3dd53b94, v146
	v_fmamk_f32 v94, v94, 0x3dd53b94, v146
	v_fmamk_f32 v95, v95, 0x3dd53b94, v146
	v_fmamk_f32 v155, v64, 0x3dd53b94, v146
	v_fmamk_f32 v156, v65, 0x3dd53b94, v146
	v_fmamk_f32 v157, v66, 0x3dd53b94, v146
	v_fmamk_f32 v158, v67, 0x3dd53b94, v146
	v_fmamk_f32 v159, v68, 0x3dd53b94, v146
	v_fmamk_f32 v148, v69, 0x3dd53b94, v146
	v_fmamk_f32 v149, v70, 0x3dd53b94, v146
	v_fmamk_f32 v150, v71, 0x3dd53b94, v146
	v_fmamk_f32 v151, v72, 0x3dd53b94, v146
	v_fmamk_f32 v152, v73, 0x3dd53b94, v146
	v_fmamk_f32 v153, v74, 0x3dd53b94, v146
	v_fmamk_f32 v154, v75, 0x3dd53b94, v146
	v_fmamk_f32 v147, v76, 0x3dd53b94, v146
	v_exp_f32_e32 v143, v81
	v_exp_f32_e32 v129, v82
	v_exp_f32_e32 v142, v83
	v_exp_f32_e32 v130, v84
	v_exp_f32_e32 v141, v85
	v_exp_f32_e32 v131, v86
	v_exp_f32_e32 v140, v87
	v_exp_f32_e32 v132, v88
	v_exp_f32_e32 v139, v89
	v_exp_f32_e32 v133, v90
	v_exp_f32_e32 v138, v91
	v_exp_f32_e32 v134, v92
	v_exp_f32_e32 v137, v93
	v_exp_f32_e32 v135, v94
	v_exp_f32_e32 v136, v95
	v_fmamk_f32 v160, v77, 0x3dd53b94, v146
	v_fmamk_f32 v161, v78, 0x3dd53b94, v146
	v_fmac_f32_e32 v146, 0x3dd53b94, v79
	s_waitcnt lgkmcnt(2)
	s_barrier
	ds_read_b128 v[64:67], v189 offset:32768
	ds_read_b128 v[68:71], v189 offset:40960
	ds_read_b128 v[240:243], v191 offset:32768
	ds_read_b128 v[244:247], v191 offset:40960
	ds_read_b128 v[248:251], v193 offset:32768
	s_cmp_lt_u32 s9, 2
	s_cselect_b32 s100, s46, s68
	s_add_i32 s100, s100, s8
	s_add_i32 s100, s100, 64
	s_ashr_i32 s101, s100, 31
	s_waitcnt lgkmcnt(4)
	v_mfma_f32_32x32x16_bf16 v[80:95], v[64:67], v[124:127], 0
	v_exp_f32_e32 v212, v154
	v_add_f32_e32 v154, 0, v128
	v_add_f32_e32 v154, v143, v154
	v_add_f32_e32 v154, v129, v154
	v_add_f32_e32 v154, v142, v154
	s_waitcnt lgkmcnt(3)
	v_mfma_f32_32x32x16_bf16 v[64:79], v[68:71], v[124:127], 0
	v_add_f32_e32 v154, v130, v154
	v_add_f32_e32 v154, v141, v154
	v_add_f32_e32 v154, v131, v154
	v_add_f32_e32 v154, v140, v154
	v_add_f32_e32 v154, v132, v154
	v_add_f32_e32 v154, v139, v154
	s_waitcnt lgkmcnt(2)
	v_mfma_f32_32x32x16_bf16 v[80:95], v[240:243], v[120:123], v[80:95]
	ds_read_b128 v[240:243], v193 offset:40960
	v_add_f32_e32 v154, v133, v154
	v_add_f32_e32 v154, v138, v154
	v_exp_f32_e32 v155, v155
	v_add_f32_e32 v154, v134, v154
	v_add_f32_e32 v154, v137, v154
	s_waitcnt lgkmcnt(2)
	v_mfma_f32_32x32x16_bf16 v[64:79], v[244:247], v[120:123], v[64:79]
	ds_read_b128 v[244:247], v195 offset:32768
	v_exp_f32_e32 v156, v156
	v_exp_f32_e32 v157, v157
	v_add_f32_e32 v154, v135, v154
	v_add_f32_e32 v154, v136, v154
	s_waitcnt lgkmcnt(2)
	v_mfma_f32_32x32x16_bf16 v[80:95], v[248:251], v[116:119], v[80:95]
	ds_read_b128 v[248:251], v195 offset:40960
	v_exp_f32_e32 v158, v158
	v_exp_f32_e32 v159, v159
	v_add_f32_e32 v154, v155, v154
	v_add_f32_e32 v154, v156, v154
	s_waitcnt lgkmcnt(2)
	v_mfma_f32_32x32x16_bf16 v[64:79], v[240:243], v[116:119], v[64:79]
	ds_read_b128 v[240:243], v196 offset:32768
	v_exp_f32_e32 v148, v148
	v_exp_f32_e32 v149, v149
	v_add_f32_e32 v154, v157, v154
	v_add_f32_e32 v154, v158, v154
	s_waitcnt lgkmcnt(2)
	v_mfma_f32_32x32x16_bf16 v[80:95], v[244:247], v[112:115], v[80:95]
	ds_read_b128 v[244:247], v196 offset:40960
	v_exp_f32_e32 v150, v150
	v_exp_f32_e32 v151, v151
	v_add_f32_e32 v154, v159, v154
	v_add_f32_e32 v154, v148, v154
	s_waitcnt lgkmcnt(2)
	v_mfma_f32_32x32x16_bf16 v[64:79], v[248:251], v[112:115], v[64:79]
	ds_read_b128 v[248:251], v194 offset:32768
	v_exp_f32_e32 v152, v152
	v_exp_f32_e32 v153, v153
	v_add_f32_e32 v154, v149, v154
	v_add_f32_e32 v154, v150, v154
	s_waitcnt lgkmcnt(2)
	v_mfma_f32_32x32x16_bf16 v[80:95], v[240:243], v[108:111], v[80:95]
	ds_read_b128 v[240:243], v194 offset:40960
	v_exp_f32_e32 v147, v147
	v_add_f32_e32 v154, v151, v154
	v_exp_f32_e32 v160, v160
	v_add_f32_e32 v154, v152, v154
	s_waitcnt lgkmcnt(2)
	v_mfma_f32_32x32x16_bf16 v[64:79], v[244:247], v[108:111], v[64:79]
	ds_read_b128 v[244:247], v192 offset:32768
	v_exp_f32_e32 v161, v161
	v_add_f32_e32 v154, v153, v154
	v_exp_f32_e32 v146, v146
	v_add_f32_e32 v154, v212, v154
	s_waitcnt lgkmcnt(2)
	v_mfma_f32_32x32x16_bf16 v[80:95], v[248:251], v[104:107], v[80:95]
	ds_read_b128 v[248:251], v192 offset:40960
	v_add_f32_e32 v154, v147, v154
	v_add_f32_e32 v154, v160, v154
	v_add_f32_e32 v154, v161, v154
	v_cvt_pk_bf16_f32 v128, v128, v143
	v_cvt_pk_bf16_f32 v129, v129, v142
	v_cvt_pk_bf16_f32 v130, v130, v141
	s_waitcnt lgkmcnt(2)
	v_mfma_f32_32x32x16_bf16 v[64:79], v[240:243], v[104:107], v[64:79]
	ds_read_b128 v[240:243], v190 offset:32768
	v_cvt_pk_bf16_f32 v131, v131, v140
	v_cvt_pk_bf16_f32 v132, v132, v139
	v_cvt_pk_bf16_f32 v133, v133, v138
	v_add_f32_e32 v222, v146, v154
	v_mov_b32_e32 v223, v222
	s_nop 1
	v_permlane32_swap_b32_e32 v222, v223
	s_waitcnt lgkmcnt(2)
	v_mfma_f32_32x32x16_bf16 v[80:95], v[244:247], v[100:103], v[80:95]
	ds_read_b128 v[244:247], v190 offset:40960
	v_permlane32_swap_b32_e32 v128, v130
	v_cvt_pk_bf16_f32 v134, v134, v137
	v_cvt_pk_bf16_f32 v135, v135, v136
	v_cvt_pk_bf16_f32 v154, v155, v156
	v_cvt_pk_bf16_f32 v155, v157, v158
	v_cvt_pk_bf16_f32 v156, v159, v148
	s_waitcnt lgkmcnt(2)
	v_mfma_f32_32x32x16_bf16 v[64:79], v[248:251], v[100:103], v[64:79]
	ds_read_b128 v[248:251], v199
	v_cvt_pk_bf16_f32 v157, v149, v150
	v_cvt_pk_bf16_f32 v224, v151, v152
	v_cvt_pk_bf16_f32 v225, v153, v212
	v_cvt_pk_bf16_f32 v226, v147, v160
	v_cvt_pk_bf16_f32 v227, v161, v146
	v_permlane32_swap_b32_e32 v129, v131
	s_waitcnt lgkmcnt(2)
	v_mfma_f32_32x32x16_bf16 v[80:95], v[240:243], v[96:99], v[80:95]
	v_permlane32_swap_b32_e32 v132, v134
	v_permlane32_swap_b32_e32 v133, v135
	v_permlane32_swap_b32_e32 v154, v156
	v_permlane32_swap_b32_e32 v155, v157
	v_permlane32_swap_b32_e32 v224, v226
	v_permlane32_swap_b32_e32 v225, v227
	s_waitcnt lgkmcnt(1)
	v_mfma_f32_32x32x16_bf16 v[64:79], v[244:247], v[96:99], v[64:79]
	ds_read_b128 v[244:247], v199 offset:4096
	ds_read_b128 v[240:243], v182
	v_lshl_add_u64 v[136:137], s[100:101], 0, v[162:163]
	v_mul_lo_u32 v138, v137, s40
	v_mul_lo_u32 v139, v136, s41
	v_mad_u64_u32 v[136:137], s[6:7], v136, s40, 0
	v_add3_u32 v137, v137, v139, v138
	v_lshl_add_u64 v[138:139], v[166:167], 0, s[100:101]
	s_waitcnt lgkmcnt(0)
	v_mfma_f32_32x32x16_bf16 v[80:95], v[248:251], v[240:243], v[80:95]
	ds_read_b128 v[248:251], v201
	v_mul_lo_u32 v140, v139, s40
	v_mul_lo_u32 v141, v138, s41
	v_mad_u64_u32 v[138:139], s[6:7], v138, s40, 0
	v_add3_u32 v139, v139, v141, v140
	v_lshlrev_b64 v[146:147], 1, v[136:137]
	v_lshlrev_b64 v[148:149], 1, v[138:139]
	v_mfma_f32_32x32x16_bf16 v[64:79], v[244:247], v[240:243], v[64:79]
	ds_read_b128 v[244:247], v201 offset:4096
	ds_read_b128 v[240:243], v182 offset:1024
	v_lshl_add_u64 v[158:159], s[100:101], 0, v[164:165]
	v_lshl_add_u64 v[136:137], v[168:169], 0, v[146:147]
	v_lshl_add_u64 v[140:141], v[168:169], 0, v[148:149]
	v_lshl_add_u64 v[146:147], v[170:171], 0, v[146:147]
	v_lshl_add_u64 v[150:151], v[170:171], 0, v[148:149]
	v_mad_u64_u32 v[160:161], s[100:101], v158, s3, v[172:173]
	s_waitcnt lgkmcnt(0)
	v_mfma_f32_32x32x16_bf16 v[80:95], v[248:251], v[240:243], v[80:95]
	ds_read_b128 v[248:251], v203
	v_mad_i32_i24 v161, v159, s3, v161
	v_mfma_f32_32x32x16_bf16 v[64:79], v[244:247], v[240:243], v[64:79]
	ds_read_b128 v[244:247], v203 offset:4096
	ds_read_b128 v[240:243], v182 offset:2048
	s_waitcnt lgkmcnt(0)
	v_mfma_f32_32x32x16_bf16 v[80:95], v[248:251], v[240:243], v[80:95]
	ds_read_b128 v[248:251], v205
	v_mfma_f32_32x32x16_bf16 v[64:79], v[244:247], v[240:243], v[64:79]
	ds_read_b128 v[244:247], v205 offset:4096
	ds_read_b128 v[240:243], v182 offset:3072
	ds_read_b64_tr_b16 v[232:233], v184 offset:0
	ds_read_b64_tr_b16 v[234:235], v184 offset:0x800
	ds_read_b64_tr_b16 v[236:237], v184 offset:0x1000
	ds_read_b64_tr_b16 v[238:239], v184 offset:0x1800
	s_waitcnt lgkmcnt(4)
	v_mfma_f32_32x32x16_bf16 v[80:95], v[248:251], v[240:243], v[80:95]
	v_mfma_f32_32x32x16_bf16 v[64:79], v[244:247], v[240:243], v[64:79]
	ds_read_b64_tr_b16 v[240:241], v184 offset:0x2000
	ds_read_b64_tr_b16 v[242:243], v184 offset:0x2800
	ds_read_b64_tr_b16 v[244:245], v184 offset:0x3000
	ds_read_b64_tr_b16 v[246:247], v184 offset:0x3800
	global_load_dwordx4 v[136:139], v[136:137], off
	global_load_dwordx4 v[140:143], v[140:141], off
	global_load_dwordx4 v[146:149], v[146:147], off
	global_load_dwordx4 v[150:153], v[150:151], off
	global_load_dwordx4 v[158:161], v[160:161], off
	s_waitcnt lgkmcnt(6)
	v_mfma_f32_32x32x16_bf16 v[0:15], v[128:131], v[232:235], v[0:15]
	ds_read_b64_tr_b16 v[232:233], v184 offset:0x200
	ds_read_b64_tr_b16 v[234:235], v184 offset:0xa00
	s_waitcnt lgkmcnt(6)
	v_mfma_f32_32x32x16_bf16 v[0:15], v[132:135], v[236:239], v[0:15]
	ds_read_b64_tr_b16 v[236:237], v184 offset:0x1200
	ds_read_b64_tr_b16 v[238:239], v184 offset:0x1a00
	v_max_f32_e32 v250, v81, v81
	v_max_f32_e32 v251, v80, v80
	v_max_f32_e32 v250, v251, v250
	v_max3_f32 v250, v250, v82, v83
	v_max3_f32 v250, v250, v84, v85
	v_max3_f32 v250, v250, v86, v87
	s_waitcnt lgkmcnt(6)
	v_mfma_f32_32x32x16_bf16 v[0:15], v[154:157], v[240:243], v[0:15]
	ds_read_b64_tr_b16 v[240:241], v184 offset:0x2200
	ds_read_b64_tr_b16 v[242:243], v184 offset:0x2a00
	v_max3_f32 v250, v250, v88, v89
	v_max3_f32 v250, v250, v90, v91
	v_max3_f32 v250, v250, v92, v93
	v_max3_f32 v250, v250, v94, v95
	v_max3_f32 v250, v250, v64, v65
	v_max3_f32 v250, v250, v66, v67
	s_waitcnt lgkmcnt(6)
	v_mfma_f32_32x32x16_bf16 v[0:15], v[224:227], v[244:247], v[0:15]
	ds_read_b64_tr_b16 v[244:245], v184 offset:0x3200
	ds_read_b64_tr_b16 v[246:247], v184 offset:0x3a00
	v_max3_f32 v250, v250, v68, v69
	v_max3_f32 v250, v250, v70, v71
	v_max3_f32 v250, v250, v72, v73
	v_max3_f32 v250, v250, v74, v75
	v_max3_f32 v250, v250, v76, v77
	v_max3_f32 v250, v250, v78, v79
	s_waitcnt lgkmcnt(6)
	v_mfma_f32_32x32x16_bf16 v[48:63], v[128:131], v[232:235], v[48:63]
	ds_read_b64_tr_b16 v[232:233], v184 offset:0x400
	ds_read_b64_tr_b16 v[234:235], v184 offset:0xc00
	v_mov_b32_e32 v251, v250
	s_nop 1
	v_permlane32_swap_b32_e32 v250, v251
	v_max_f32_e32 v251, v251, v251
	v_max_f32_e32 v250, v250, v250
	v_max_f32_e32 v250, v250, v251
	v_sub_f32_e32 v251, v250, v207
	s_waitcnt lgkmcnt(6)
	v_mfma_f32_32x32x16_bf16 v[48:63], v[132:135], v[236:239], v[48:63]
	ds_read_b64_tr_b16 v[236:237], v184 offset:0x1400
	ds_read_b64_tr_b16 v[238:239], v184 offset:0x1c00
	v_cmp_ge_f32_e32 vcc, s94, v251
	v_max_f32_e32 v251, v207, v207
	v_max_f32_e32 v250, v251, v250
	v_sub_f32_e32 v251, v207, v250
	v_mul_f32_e32 v251, 0x3dd53b94, v251
	s_waitcnt lgkmcnt(6)
	v_mfma_f32_32x32x16_bf16 v[48:63], v[154:157], v[240:243], v[48:63]
	ds_read_b64_tr_b16 v[240:241], v184 offset:0x2400
	ds_read_b64_tr_b16 v[242:243], v184 offset:0x2c00
	v_exp_f32_e32 v251, v251
	s_waitcnt lgkmcnt(6)
	v_mfma_f32_32x32x16_bf16 v[48:63], v[224:227], v[244:247], v[48:63]
	ds_read_b64_tr_b16 v[244:245], v184 offset:0x3400
	ds_read_b64_tr_b16 v[246:247], v184 offset:0x3c00
	s_waitcnt lgkmcnt(6)
	v_mfma_f32_32x32x16_bf16 v[32:47], v[128:131], v[232:235], v[32:47]
	ds_read_b64_tr_b16 v[232:233], v184 offset:0x600
	ds_read_b64_tr_b16 v[234:235], v184 offset:0xe00
	s_waitcnt lgkmcnt(6)
	v_mfma_f32_32x32x16_bf16 v[32:47], v[132:135], v[236:239], v[32:47]
	ds_read_b64_tr_b16 v[236:237], v184 offset:0x1600
	ds_read_b64_tr_b16 v[238:239], v184 offset:0x1e00
	s_waitcnt lgkmcnt(6)
	v_mfma_f32_32x32x16_bf16 v[32:47], v[154:157], v[240:243], v[32:47]
	ds_read_b64_tr_b16 v[240:241], v184 offset:0x2600
	ds_read_b64_tr_b16 v[242:243], v184 offset:0x2e00
	s_waitcnt lgkmcnt(6)
	v_mfma_f32_32x32x16_bf16 v[32:47], v[224:227], v[244:247], v[32:47]
	ds_read_b64_tr_b16 v[244:245], v184 offset:0x3600
	ds_read_b64_tr_b16 v[246:247], v184 offset:0x3e00
	s_waitcnt lgkmcnt(6)
	v_mfma_f32_32x32x16_bf16 v[16:31], v[128:131], v[232:235], v[16:31]
	s_waitcnt lgkmcnt(4)
	v_mfma_f32_32x32x16_bf16 v[16:31], v[132:135], v[236:239], v[16:31]
	s_waitcnt lgkmcnt(2)
	v_mfma_f32_32x32x16_bf16 v[16:31], v[154:157], v[240:243], v[16:31]
	s_waitcnt lgkmcnt(0)
	v_mfma_f32_32x32x16_bf16 v[16:31], v[224:227], v[244:247], v[16:31]
	s_cmp_eq_u64 vcc, exec
	s_cselect_b64 s[6:7], -1, 0
	s_barrier
	s_waitcnt vmcnt(0)
	v_cndmask_b32_e64 v221, v251, 1.0, s[6:7]
	v_cmp_gt_f32_e32 vcc, 1.0, v221
	ds_write_b128 v187, v[146:149] offset:49152
	ds_write_b128 v188, v[150:153] offset:49152
	ds_write_b128 v209, v[158:161]
	ds_write_b128 v185, v[136:139] offset:16384
	ds_write_b128 v186, v[140:143] offset:16384
	s_nop 0
	s_nop 0
	s_nop 0
	s_nop 0
	s_nop 0
	s_cbranch_vccz .LBB0_770
	s_and_saveexec_b64 s[0:1], s[4:5]
	ds_write_b32 v183, v221 offset:128
	s_or_b64 exec, exec, s[0:1]
	s_waitcnt lgkmcnt(0)
	v_add_u32_e32 v129, v180, v144
	ds_read_b128 v[130:133], v129 offset:224
	ds_read_b128 v[134:137], v129 offset:192
	ds_read_b128 v[138:141], v129 offset:160
	ds_read_b128 v[146:149], v129 offset:128
	s_waitcnt lgkmcnt(3)
	v_pk_mul_f32 v[12:13], v[12:13], v[130:131]
	s_waitcnt lgkmcnt(2)
	v_pk_mul_f32 v[8:9], v[8:9], v[134:135]
	s_waitcnt lgkmcnt(1)
	v_pk_mul_f32 v[4:5], v[4:5], v[138:139]
	v_pk_mul_f32 v[14:15], v[14:15], v[132:133]
	v_pk_mul_f32 v[10:11], v[10:11], v[136:137]
	v_pk_mul_f32 v[6:7], v[6:7], v[140:141]
	s_waitcnt lgkmcnt(0)
	v_pk_mul_f32 v[2:3], v[2:3], v[148:149]
	v_pk_mul_f32 v[0:1], v[0:1], v[146:147]
	v_pk_mul_f32 v[60:61], v[60:61], v[130:131]
	v_pk_mul_f32 v[56:57], v[56:57], v[134:135]
	v_pk_mul_f32 v[52:53], v[52:53], v[138:139]
	v_pk_mul_f32 v[62:63], v[62:63], v[132:133]
	v_pk_mul_f32 v[58:59], v[58:59], v[136:137]
	v_pk_mul_f32 v[54:55], v[54:55], v[140:141]
	v_pk_mul_f32 v[50:51], v[50:51], v[148:149]
	v_pk_mul_f32 v[48:49], v[48:49], v[146:147]
	v_pk_mul_f32 v[44:45], v[44:45], v[130:131]
	v_pk_mul_f32 v[40:41], v[40:41], v[134:135]
	v_pk_mul_f32 v[36:37], v[36:37], v[138:139]
	v_pk_mul_f32 v[46:47], v[46:47], v[132:133]
	v_pk_mul_f32 v[42:43], v[42:43], v[136:137]
	v_pk_mul_f32 v[38:39], v[38:39], v[140:141]
	v_pk_mul_f32 v[34:35], v[34:35], v[148:149]
	v_pk_mul_f32 v[32:33], v[32:33], v[146:147]
	v_pk_mul_f32 v[28:29], v[28:29], v[130:131]
	v_pk_mul_f32 v[24:25], v[24:25], v[134:135]
	v_pk_mul_f32 v[20:21], v[20:21], v[138:139]
	v_pk_mul_f32 v[30:31], v[30:31], v[132:133]
	v_pk_mul_f32 v[26:27], v[26:27], v[136:137]
	v_pk_mul_f32 v[22:23], v[22:23], v[140:141]
	v_pk_mul_f32 v[18:19], v[18:19], v[148:149]
	v_pk_mul_f32 v[16:17], v[16:17], v[146:147]
